# plus scan loaders: running pointers carry workspace base + region offset + 16-byte lane offset (no per-chunk 64-bit address arithmetic)
# baseline (speedup 1.0000x reference)
; __device__ __forceinline__ void scan_phase(const Params& P, int l, LAS unsigned char* lds) {
;     ...
;                     if (jl < NT) {
;                         const int n0 = jl * TS; const int plo = dir ? (n0 < 256 ? 256 - TS - n0 : TPB + 256 - TS - n0) : n0;
;                         const size_t task = (size_t)grp * NCHUNK + jl;
;                         const unsigned char* cq = ws + WS_HGQ + task * 4096; const unsigned char* ck = ws + WS_HGK + task * 4096; const unsigned char* ca = ws + WS_HGA + task * 1024;
; #pragma unroll
;                         for (int j = 0; j < 4; ++j) fq[j] = *(const u32x4*)(cq + (size_t)(j * 64 + lane) * 16);
; #pragma unroll
;                         for (int m = 0; m < 8; ++m) fk[m] = *(const u32x2*)(ck + (size_t)(m * 64 + lane) * 8);
;                         fa = *(const u32x2*)(ca + (size_t)lane * 8);
;                         if (lane < 32) p15 = *(const f32x4*)(ca + 512 + (size_t)lane * 16);
.LBB0_673:
	s_lshl_b32 s8, s54, 2
	s_and_b32 s73, s8, 28
	s_ashr_i32 s8, s54, 6
	s_add_i32 s73, s73, s8
	s_ashr_i32 s9, s73, 4
	s_and_b32 s57, s8, 1
	s_lshl_b32 s8, s54, 1
	s_bfe_u32 s55, s73, 0x30001
	s_and_b32 s56, s8, 0x70
	s_mul_hi_i32 s17, s9, 0x1100
	s_mul_i32 s16, s9, 0x1100
	s_mov_b64 s[8:9], -1
	s_and_b64 vcc, exec, s[10:11]
	s_cbranch_vccz .LBB0_782
	s_and_b64 vcc, exec, s[36:37]
	s_cbranch_vccz .LBB0_776
	v_readlane_b32 s8, v252, 0
	v_readlane_b32 s9, v252, 1
	s_load_dword s8, s[8:9], 0x10
	v_readlane_b32 s12, v250, 32
	v_readlane_b32 s13, v250, 33
	s_mov_b64 s[18:19], -1
	s_mul_hi_i32 s82, s73, 0x110000
	s_waitcnt lgkmcnt(0)
	s_lshr_b32 s8, s8, 16
	s_cmp_lg_u32 s8, 0
	s_cselect_b64 s[8:9], -1, 0
	s_cmp_lg_u64 s[8:9], 0
	s_addc_u32 s72, s49, 0
	s_cmp_eq_u32 s57, 0
	s_cselect_b64 s[8:9], -1, 0
	s_lshl_b32 s80, s55, 7
	s_and_b64 vcc, exec, s[12:13]
	s_mul_i32 s83, s73, 0x110000
	s_cbranch_vccz .LBB0_726
	s_lshl_b32 s14, s80, 1
	v_readlane_b32 s15, v253, 40
	s_add_u32 s14, s15, s14
	v_readlane_b32 s15, v253, 41
	s_addc_u32 s15, s15, 0
	s_lshl_b32 s18, s56, 1
	s_add_u32 s14, s14, s18
	s_addc_u32 s15, s15, 0
	v_lshlrev_b32_e32 v2, 1, v44
	s_waitcnt vmcnt(20)
	v_lshl_add_u64 v[24:25], s[14:15], 0, v[2:3]
	v_mov_b32_e32 v2, v3
	s_waitcnt vmcnt(13)
	v_mov_b32_e32 v6, v3
	v_mov_b32_e32 v7, v3
	s_waitcnt vmcnt(4)
	v_mov_b32_e32 v0, v3
	v_mov_b32_e32 v1, v3
	v_mov_b32_e32 v34, v3
	v_mov_b32_e32 v35, v3
	v_mov_b32_e32 v4, v3
	v_mov_b32_e32 v5, v3
	v_mov_b64_e32 v[10:11], v[6:7]
	v_mov_b64_e32 v[14:15], v[6:7]
	v_mov_b64_e32 v[18:19], v[6:7]
	v_mov_b64_e32 v[22:23], v[2:3]
	s_movk_i32 s12, 0x11f0
	v_mad_i64_i32 v[26:27], s[14:15], s73, v232, v[54:55]
	v_mad_i64_i32 v[28:29], s[14:15], s73, v232, v[56:57]
	v_mov_b32_e32 v31, s82
	v_or_b32_e32 v30, s83, v46
	v_mov_b32_e32 v33, s82
	v_or_b32_e32 v32, s83, v46
	v_readlane_b32 s22, v252, 2
	v_readlane_b32 s23, v252, 3
	s_nop 3
	v_add_u32_e32 v26, v48, v26
	v_lshl_add_u64 v[26:27], s[22:23], 0, v[26:27]
	s_add_u32 s20, s22, 0x2bd40000
	s_addc_u32 s21, s23, 0
	v_lshl_add_u64 v[30:31], s[20:21], 0, v[30:31]
	s_add_u32 s20, s22, 0x41d60000
	s_addc_u32 s21, s23, 0
	v_lshl_add_u64 v[32:33], s[20:21], 0, v[32:33]
	s_mov_b32 s81, 0
	s_mov_b64 s[18:19], 0
	s_mov_b32 s89, -4
	s_waitcnt vmcnt(0)
	v_mov_b32_e32 v66, 0
	v_mov_b32_e32 v70, 0
	s_mov_b32 s92, 0
	s_mov_b32 s93, 0
	v_mov_b64_e32 v[8:9], v[4:5]
	v_mov_b64_e32 v[12:13], v[4:5]
	v_mov_b64_e32 v[16:17], v[4:5]
	v_mov_b64_e32 v[36:37], v[34:35]
	v_mov_b64_e32 v[38:39], v[34:35]
	v_mov_b64_e32 v[40:41], v[34:35]
	v_mov_b64_e32 v[42:43], v[34:35]
	v_mov_b64_e32 v[60:61], v[34:35]
	v_mov_b64_e32 v[62:63], v[34:35]
	v_mov_b64_e32 v[64:65], v[34:35]
	v_mov_b32_e32 v69, 0
	v_mov_b32_e32 v68, 0
	v_mov_b32_e32 v47, 0
	v_mov_b32_e32 v110, 0
	v_mov_b32_e32 v109, 0
	v_mov_b32_e32 v108, 0
	v_mov_b32_e32 v107, 0
	v_mov_b32_e32 v106, 0
	v_mov_b32_e32 v105, 0
	v_mov_b32_e32 v104, 0
	v_mov_b32_e32 v103, 0
	v_mov_b32_e32 v102, 0
	v_mov_b32_e32 v101, 0
	v_mov_b32_e32 v100, 0
	v_mov_b32_e32 v99, 0
	v_mov_b32_e32 v89, 0
	v_mov_b32_e32 v88, 0
	v_mov_b32_e32 v87, 0
	v_mov_b32_e32 v86, 0
	v_mov_b32_e32 v85, 0
	v_mov_b32_e32 v84, 0
	v_mov_b32_e32 v83, 0
	v_mov_b32_e32 v82, 0
	v_mov_b32_e32 v81, 0
	v_mov_b32_e32 v80, 0
	v_mov_b32_e32 v79, 0
	v_mov_b32_e32 v78, 0
	v_mov_b32_e32 v77, 0
	v_mov_b32_e32 v76, 0
	v_mov_b32_e32 v75, 0
	v_mov_b32_e32 v74, 0
	v_mov_b32_e32 v73, 0
	v_mov_b32_e32 v72, 0
	v_mov_b32_e32 v71, 0
	s_mov_b32 s97, 0
	v_mov_b64_e32 v[20:21], v[0:1]
	v_mov_b64_e32 v[0:1], v[34:35]
	s_branch .LBB0_681

; __device__ __forceinline__ void scan_phase(const Params& P, int l, LAS unsigned char* lds) {
;     ...
;                         const unsigned char* cq = ws + WS_HGQ + task * 4096; const unsigned char* ck = ws + WS_HGK + task * 4096; const unsigned char* ca = ws + WS_HGA + task * 1024;
; #pragma unroll
;                         for (int j = 0; j < 4; ++j) fq[j] = *(const u32x4*)(cq + (size_t)(j * 64 + lane) * 16);
; #pragma unroll
;                         for (int m = 0; m < 8; ++m) fk[m] = *(const u32x2*)(ck + (size_t)(m * 64 + lane) * 8);
;                         fa = *(const u32x2*)(ca + (size_t)lane * 8);
;                         if (lane < 32) p15 = *(const f32x4*)(ca + 512 + (size_t)lane * 16);
.LBB0_686:
	s_cmpk_gt_i32 s89, 0x10b
	s_cbranch_scc1 .LBB0_690
	s_waitcnt vmcnt(4)
	global_load_dwordx4 v[16:19], v[30:31], off
	global_load_dwordx4 v[12:15], v[30:31], off offset:1024
	global_load_dwordx4 v[8:11], v[30:31], off offset:2048
	global_load_dwordx4 v[4:7], v[30:31], off offset:3072
	global_load_dwordx4 v[176:179], v[32:33], off
	global_load_dwordx4 v[180:183], v[32:33], off offset:1024
	global_load_dwordx4 v[184:187], v[32:33], off offset:2048
	global_load_dwordx4 v[188:191], v[32:33], off offset:3072
	global_load_dwordx4 v[192:195], v[26:27], off

; __device__ __forceinline__ void scan_phase(const Params& P, int l, LAS unsigned char* lds) {
;     ...
;                     if (jl < NT) {
;                         const int n0 = jl * TS; const int plo = dir ? (n0 < 256 ? 256 - TS - n0 : TPB + 256 - TS - n0) : n0;
;                         const size_t task = (size_t)grp * NCHUNK + jl;
;                         const unsigned char* c1 = ws + WS_CP1 + task * CP1_STRIDE; const unsigned char* ck = ws + WS_CPK + task * 4096; const unsigned char* c2 = ws + WS_CP2 + task * CP2_STRIDE;
; #pragma unroll
;                         for (int j = 0; j < 4; ++j) { fw[j] = *(const u32x4*)(c1 + (size_t)(j * 64 + lane) * 16); fq[j] = *(const u32x4*)(c1 + 4096 + (size_t)(j * 64 + lane) * 16); }
; #pragma unroll
;                         for (int m = 0; m < 8; ++m) fk[m] = *(const u32x2*)(ck + (size_t)(m * 64 + lane) * 8);
;                         fa = *(const u32x2*)(c2 + (size_t)lane * 8); ft = *(const u32x2*)(c2 + 512 + (size_t)lane * 8);
;                         b4 = *(const f32x4*)(c2 + 1024 + quad * 16); egC = *(const float*)(c2 + 1024 + 64);
.LBB0_726:
	s_and_b64 vcc, exec, s[18:19]
	s_cbranch_vccz .LBB0_775
	s_lshl_b32 s14, s80, 2
	v_readlane_b32 s15, v253, 21
	s_add_u32 s14, s15, s14
	v_readlane_b32 s15, v253, 22
	s_addc_u32 s15, s15, 0
	s_lshl_b32 s18, s56, 2
	s_add_u32 s14, s14, s18
	s_addc_u32 s15, s15, 0
	v_lshlrev_b32_e32 v2, 2, v44
	s_waitcnt vmcnt(10)
	v_lshl_add_u64 v[60:61], s[14:15], 0, v[2:3]
	s_mul_i32 s19, s73, 0x4c800
	v_mad_i64_i32 v[62:63], s[14:15], s73, v233, v[58:59]
	v_mov_b32_e32 v2, v3
	v_mov_b32_e32 v8, v3
	v_mov_b32_e32 v9, v3
	v_mov_b32_e32 v10, v3
	v_mov_b32_e32 v11, v3
	s_mul_hi_i32 s18, s73, 0x4c800
	s_add_u32 s80, s19, 0x413d0440
	s_mul_hi_i32 s14, s73, 0x220000
	s_mul_i32 s73, s73, 0x220000
	s_waitcnt vmcnt(4)
	v_mov_b32_e32 v0, v3
	v_mov_b32_e32 v1, v3
	s_waitcnt vmcnt(0)
	v_mov_b32_e32 v70, v3
	v_mov_b32_e32 v71, v3
	v_mov_b32_e32 v130, 0
	v_mov_b64_e32 v[22:23], v[10:11]
	v_mov_b64_e32 v[18:19], v[10:11]
	v_mov_b64_e32 v[4:5], v[8:9]
	v_mov_b64_e32 v[34:35], v[10:11]
	v_mov_b64_e32 v[30:31], v[10:11]
	v_mov_b64_e32 v[26:27], v[10:11]
	v_mov_b64_e32 v[14:15], v[10:11]
	v_mov_b64_e32 v[38:39], v[2:3]
	v_mov_b32_e32 v65, s18
	v_or_b32_e32 v64, s19, v46
	s_addc_u32 s81, s18, 0
	v_mov_b32_e32 v67, s82
	v_or_b32_e32 v66, s83, v46
	v_mov_b32_e32 v69, s14
	v_or_b32_e32 v68, s73, v46
	v_readlane_b32 s22, v252, 2
	v_readlane_b32 s23, v252, 3
	s_nop 3
	s_add_u32 s20, s22, 0x38b60000
	s_addc_u32 s21, s23, 0
	v_lshl_add_u64 v[68:69], s[20:21], 0, v[68:69]
	s_add_u32 s20, s22, 0x17600000
	s_addc_u32 s21, s23, 0
	v_lshl_add_u64 v[66:67], s[20:21], 0, v[66:67]
	s_add_u32 s20, s22, 0x413d0000
	s_addc_u32 s21, s23, 0
	v_lshl_add_u64 v[64:65], s[20:21], 0, v[64:65]
	v_lshl_add_u64 v[62:63], s[22:23], 0, v[62:63]
	s_mov_b32 s73, 0
	s_mov_b32 s82, -4
	s_mov_b64 s[18:19], 0
	s_mov_b32 s83, 0
	s_mov_b32 s89, 0
	v_mov_b64_e32 v[20:21], v[8:9]
	v_mov_b64_e32 v[16:17], v[8:9]
	v_mov_b64_e32 v[6:7], v[10:11]
	v_mov_b64_e32 v[32:33], v[8:9]
	v_mov_b64_e32 v[28:29], v[8:9]
	v_mov_b64_e32 v[24:25], v[8:9]
	v_mov_b64_e32 v[12:13], v[8:9]
	v_mov_b64_e32 v[72:73], v[70:71]
	v_mov_b64_e32 v[74:75], v[70:71]
	v_mov_b64_e32 v[76:77], v[70:71]
	v_mov_b64_e32 v[78:79], v[70:71]
	v_mov_b64_e32 v[80:81], v[70:71]
	v_mov_b64_e32 v[82:83], v[70:71]
	v_mov_b64_e32 v[84:85], v[70:71]
	v_mov_b32_e32 v129, 0
	v_mov_b32_e32 v128, 0
	v_mov_b32_e32 v127, 0
	v_mov_b32_e32 v126, 0
	v_mov_b32_e32 v125, 0
	v_mov_b32_e32 v124, 0
	v_mov_b32_e32 v123, 0
	v_mov_b32_e32 v122, 0
	v_mov_b32_e32 v121, 0
	v_mov_b32_e32 v120, 0
	v_mov_b32_e32 v119, 0
	v_mov_b32_e32 v118, 0
	v_mov_b32_e32 v117, 0
	v_mov_b32_e32 v116, 0
	v_mov_b32_e32 v115, 0
	v_mov_b32_e32 v114, 0
	v_mov_b32_e32 v113, 0
	v_mov_b32_e32 v112, 0
	v_mov_b32_e32 v111, 0
	v_mov_b32_e32 v110, 0
	v_mov_b32_e32 v109, 0
	v_mov_b32_e32 v108, 0
	v_mov_b32_e32 v107, 0
	v_mov_b32_e32 v106, 0
	v_mov_b32_e32 v105, 0
	v_mov_b32_e32 v104, 0
	v_mov_b32_e32 v103, 0
	v_mov_b32_e32 v102, 0
	v_mov_b32_e32 v101, 0
	v_mov_b32_e32 v100, 0
	v_mov_b32_e32 v99, 0
	v_mov_b64_e32 v[86:87], v[70:71]
	v_mov_b64_e32 v[88:89], v[70:71]
	v_mov_b64_e32 v[36:37], v[0:1]
	v_mov_b32_e32 v47, 0
	s_mov_b32 s92, 0
	v_mov_b32_e32 v40, 0
	v_mov_b32_e32 v41, v130
	v_mov_b32_e32 v42, v130
	v_mov_b32_e32 v43, v130
	s_branch .LBB0_733

; __device__ __forceinline__ void scan_phase(const Params& P, int l, LAS unsigned char* lds) {
;     ...
;                         const int n0 = jl * TS; const int plo = dir ? (n0 < 256 ? 256 - TS - n0 : TPB + 256 - TS - n0) : n0;
;                         const size_t task = (size_t)grp * NCHUNK + jl;
;                         const unsigned char* c1 = ws + WS_CP1 + task * CP1_STRIDE; const unsigned char* ck = ws + WS_CPK + task * 4096; const unsigned char* c2 = ws + WS_CP2 + task * CP2_STRIDE;
; #pragma unroll
;                         for (int j = 0; j < 4; ++j) { fw[j] = *(const u32x4*)(c1 + (size_t)(j * 64 + lane) * 16); fq[j] = *(const u32x4*)(c1 + 4096 + (size_t)(j * 64 + lane) * 16); }
; #pragma unroll
;                         for (int m = 0; m < 8; ++m) fk[m] = *(const u32x2*)(ck + (size_t)(m * 64 + lane) * 8);
;                         fa = *(const u32x2*)(c2 + (size_t)lane * 8); ft = *(const u32x2*)(c2 + 512 + (size_t)lane * 8);
;                         b4 = *(const f32x4*)(c2 + 1024 + quad * 16); egC = *(const float*)(c2 + 1024 + 64);
; #pragma unroll
;                         for (int e = 0; e < 4; ++e) { const int s = 4 * quad + e; const int p = dir ? plo + TS - 1 - s : plo + s;
;                             v4[e] = DNV[(rowbase + p) * 1024 + h * 128 + col0 + col]; }
.LBB0_738:
	s_cmpk_gt_i32 s82, 0x10b
	s_cbranch_scc1 .LBB0_740
	v_readlane_b32 s22, v252, 2
	v_readlane_b32 s23, v252, 3
	s_cmp_lt_i32 s82, 12
	s_cselect_b32 s15, 0xf0, s93
	v_lshl_add_u64 v[0:1], v[68:69], 0, s[74:75]
	s_waitcnt vmcnt(17)
	s_add_i32 s15, s15, s83
	global_load_dwordx4 v[4:7], v[68:69], off
	global_load_dwordx4 v[12:15], v[0:1], off
	global_load_dwordx4 v[16:19], v[68:69], off offset:1024
	global_load_dwordx4 v[24:27], v[0:1], off offset:1024
	global_load_dwordx4 v[20:23], v[68:69], off offset:2048
	global_load_dwordx4 v[28:31], v[0:1], off offset:2048
	s_nop 0
	global_load_dwordx4 v[8:11], v[68:69], off offset:3072
	s_nop 0
	global_load_dwordx4 v[32:35], v[0:1], off offset:3072
	s_and_b64 s[20:21], s[8:9], exec
	global_load_dwordx4 v[156:159], v[66:67], off
	global_load_dwordx4 v[160:163], v[66:67], off offset:1024
	global_load_dwordx4 v[164:167], v[66:67], off offset:2048
	global_load_dwordx4 v[168:171], v[66:67], off offset:3072
	s_cselect_b32 s15, s89, s15
	s_add_u32 s20, s22, s80
	global_load_dwordx4 v[172:175], v[64:65], off
	s_addc_u32 s21, s23, s81
	s_or_b32 s15, s15, 15
	global_load_dwordx4 v[36:39], v[62:63], off
	global_load_dword v47, v3, s[20:21]
	v_sub_u32_e32 v0, s15, v45
	v_add_u32_e32 v2, s89, v45
	v_cndmask_b32_e64 v0, v0, v2, s[8:9]
	v_ashrrev_i32_e32 v1, 31, v0
	v_lshl_add_u64 v[0:1], s[16:17], 0, v[0:1]
	v_lshlrev_b64 v[0:1], 12, v[0:1]
	v_lshl_add_u64 v[0:1], v[60:61], 0, v[0:1]
	global_load_dword v40, v[0:1], off
	s_and_b64 s[20:21], s[8:9], exec
	s_mov_b32 s20, 0xfffff000
	s_cselect_b32 s20, 0x1000, s20
	s_cselect_b32 s21, 0, -1
	v_lshl_add_u64 v[0:1], v[0:1], 0, s[20:21]
	global_load_dword v41, v[0:1], off
	v_lshl_add_u64 v[0:1], v[0:1], 0, s[20:21]
	global_load_dword v42, v[0:1], off
	v_lshl_add_u64 v[0:1], v[0:1], 0, s[20:21]
	global_load_dword v43, v[0:1], off
